# residual epilogue of a full unit hand-written: source loads of row group g+1 in flight while group g is scaled, added and stored
# baseline (speedup 1.0000x reference)
;     __device__ __forceinline__ void operator()(const f32x4 (&acc)[2][2][4][2], const Unit& u, int wr, int wc, int fr, int fq) const {
;     ...
; #pragma unroll
;         for (int ai = 0; ai < 2; ++ai)
; #pragma unroll
;             for (int m = 0; m < 4; ++m) {
;                 const int ro = (ai * 128 + m * 16) * DM;
;                 f32x4 s[2][2];
; #pragma unroll
;                 for (int bj = 0; bj < 2; ++bj)
; #pragma unroll
;                     for (int n = 0; n < 2; ++n) s[bj][n] = *(const f32x4*)(sp + ro + bj * 128 + n * 4);
; #pragma unroll
;                 for (int bj = 0; bj < 2; ++bj)
; #pragma unroll
;                     for (int n = 0; n < 2; ++n) *(f32x4*)(dp + ro + bj * 128 + n * 4) = s[bj][n] + gv[bj][n] * acc[ai][bj][m][n];
;                 asm volatile("" ::: "memory");
;             }
.Lkq_epi_full:
	s_mov_b64 s[48:49], 0x0
	v_lshl_add_u64 v[230:231], v[156:157], 0, s[48:49]
	global_load_dwordx4 v[166:169], v[230:231], off
	global_load_dwordx4 v[170:173], v[230:231], off offset:16
	global_load_dwordx4 v[174:177], v[230:231], off offset:512
	global_load_dwordx4 v[178:181], v[230:231], off offset:528
	s_mov_b64 s[48:49], 0x10000
	v_lshl_add_u64 v[232:233], v[156:157], 0, s[48:49]
	global_load_dwordx4 v[208:211], v[232:233], off
	global_load_dwordx4 v[212:215], v[232:233], off offset:16
	global_load_dwordx4 v[216:219], v[232:233], off offset:512
	global_load_dwordx4 v[220:223], v[232:233], off offset:528
	s_waitcnt vmcnt(4)
	v_pk_fma_f32 v[126:127], v[126:127], v[160:161], v[166:167]
	v_pk_fma_f32 v[128:129], v[128:129], v[158:159], v[168:169]
	v_pk_fma_f32 v[122:123], v[122:123], v[144:145], v[170:171]
	v_pk_fma_f32 v[124:125], v[124:125], v[136:137], v[172:173]
	v_pk_fma_f32 v[118:119], v[118:119], v[154:155], v[174:175]
	v_pk_fma_f32 v[120:121], v[120:121], v[152:153], v[176:177]
	v_pk_fma_f32 v[114:115], v[114:115], v[150:151], v[178:179]
	v_pk_fma_f32 v[116:117], v[116:117], v[148:149], v[180:181]
	s_mov_b64 s[48:49], 0x0
	v_lshl_add_u64 v[234:235], v[162:163], 0, s[48:49]
	global_store_dwordx4 v[234:235], v[126:129], off
	global_store_dwordx4 v[234:235], v[122:125], off offset:16
	global_store_dwordx4 v[234:235], v[118:121], off offset:512
	global_store_dwordx4 v[234:235], v[114:117], off offset:528
	s_mov_b64 s[48:49], 0x20000
	v_lshl_add_u64 v[230:231], v[156:157], 0, s[48:49]
	global_load_dwordx4 v[166:169], v[230:231], off
	global_load_dwordx4 v[170:173], v[230:231], off offset:16
	global_load_dwordx4 v[174:177], v[230:231], off offset:512
	global_load_dwordx4 v[178:181], v[230:231], off offset:528
	s_waitcnt vmcnt(8)
	v_pk_fma_f32 v[110:111], v[110:111], v[160:161], v[208:209]
	v_pk_fma_f32 v[112:113], v[112:113], v[158:159], v[210:211]
	v_pk_fma_f32 v[106:107], v[106:107], v[144:145], v[212:213]
	v_pk_fma_f32 v[108:109], v[108:109], v[136:137], v[214:215]
	v_pk_fma_f32 v[102:103], v[102:103], v[154:155], v[216:217]
	v_pk_fma_f32 v[104:105], v[104:105], v[152:153], v[218:219]
	v_pk_fma_f32 v[98:99], v[98:99], v[150:151], v[220:221]
	v_pk_fma_f32 v[100:101], v[100:101], v[148:149], v[222:223]
	s_mov_b64 s[48:49], 0x10000
	v_lshl_add_u64 v[234:235], v[162:163], 0, s[48:49]
	global_store_dwordx4 v[234:235], v[110:113], off
	global_store_dwordx4 v[234:235], v[106:109], off offset:16
	global_store_dwordx4 v[234:235], v[102:105], off offset:512
	global_store_dwordx4 v[234:235], v[98:101], off offset:528
	s_mov_b64 s[48:49], 0x30000
	v_lshl_add_u64 v[232:233], v[156:157], 0, s[48:49]
	global_load_dwordx4 v[208:211], v[232:233], off
	global_load_dwordx4 v[212:215], v[232:233], off offset:16
	global_load_dwordx4 v[216:219], v[232:233], off offset:512
	global_load_dwordx4 v[220:223], v[232:233], off offset:528
	s_waitcnt vmcnt(8)
	v_pk_fma_f32 v[94:95], v[94:95], v[160:161], v[166:167]
	v_pk_fma_f32 v[96:97], v[96:97], v[158:159], v[168:169]
	v_pk_fma_f32 v[90:91], v[90:91], v[144:145], v[170:171]
	v_pk_fma_f32 v[92:93], v[92:93], v[136:137], v[172:173]
	v_pk_fma_f32 v[86:87], v[86:87], v[154:155], v[174:175]
	v_pk_fma_f32 v[88:89], v[88:89], v[152:153], v[176:177]
	v_pk_fma_f32 v[82:83], v[82:83], v[150:151], v[178:179]
	v_pk_fma_f32 v[84:85], v[84:85], v[148:149], v[180:181]
	s_mov_b64 s[48:49], 0x20000
	v_lshl_add_u64 v[234:235], v[162:163], 0, s[48:49]
	global_store_dwordx4 v[234:235], v[94:97], off
	global_store_dwordx4 v[234:235], v[90:93], off offset:16
	global_store_dwordx4 v[234:235], v[86:89], off offset:512
	global_store_dwordx4 v[234:235], v[82:85], off offset:528
	s_mov_b64 s[48:49], 0x80000
	v_lshl_add_u64 v[230:231], v[156:157], 0, s[48:49]
	global_load_dwordx4 v[166:169], v[230:231], off
	global_load_dwordx4 v[170:173], v[230:231], off offset:16
	global_load_dwordx4 v[174:177], v[230:231], off offset:512
	global_load_dwordx4 v[178:181], v[230:231], off offset:528
	s_waitcnt vmcnt(8)
;     __device__ __forceinline__ void operator()(const f32x4 (&acc)[2][2][4][2], const Unit& u, int wr, int wc, int fr, int fq) const {
;     ...
; #pragma unroll
;         for (int ai = 0; ai < 2; ++ai)
; #pragma unroll
;             for (int m = 0; m < 4; ++m) {
;                 const int ro = (ai * 128 + m * 16) * DM;
;                 f32x4 s[2][2];
; #pragma unroll
;                 for (int bj = 0; bj < 2; ++bj)
; #pragma unroll
;                     for (int n = 0; n < 2; ++n) s[bj][n] = *(const f32x4*)(sp + ro + bj * 128 + n * 4);
; #pragma unroll
;                 for (int bj = 0; bj < 2; ++bj)
; #pragma unroll
;                     for (int n = 0; n < 2; ++n) *(f32x4*)(dp + ro + bj * 128 + n * 4) = s[bj][n] + gv[bj][n] * acc[ai][bj][m][n];
;                 asm volatile("" ::: "memory");
;             }
	v_pk_fma_f32 v[78:79], v[78:79], v[160:161], v[208:209]
	v_pk_fma_f32 v[80:81], v[80:81], v[158:159], v[210:211]
	v_pk_fma_f32 v[74:75], v[74:75], v[144:145], v[212:213]
	v_pk_fma_f32 v[76:77], v[76:77], v[136:137], v[214:215]
	v_pk_fma_f32 v[70:71], v[70:71], v[154:155], v[216:217]
	v_pk_fma_f32 v[72:73], v[72:73], v[152:153], v[218:219]
	v_pk_fma_f32 v[66:67], v[66:67], v[150:151], v[220:221]
	v_pk_fma_f32 v[68:69], v[68:69], v[148:149], v[222:223]
	s_mov_b64 s[48:49], 0x30000
	v_lshl_add_u64 v[234:235], v[162:163], 0, s[48:49]
	global_store_dwordx4 v[234:235], v[78:81], off
	global_store_dwordx4 v[234:235], v[74:77], off offset:16
	global_store_dwordx4 v[234:235], v[70:73], off offset:512
	global_store_dwordx4 v[234:235], v[66:69], off offset:528
	s_mov_b64 s[48:49], 0x90000
	v_lshl_add_u64 v[232:233], v[156:157], 0, s[48:49]
	global_load_dwordx4 v[208:211], v[232:233], off
	global_load_dwordx4 v[212:215], v[232:233], off offset:16
	global_load_dwordx4 v[216:219], v[232:233], off offset:512
	global_load_dwordx4 v[220:223], v[232:233], off offset:528
	s_waitcnt vmcnt(8)
	v_pk_fma_f32 v[62:63], v[62:63], v[160:161], v[166:167]
	v_pk_fma_f32 v[64:65], v[64:65], v[158:159], v[168:169]
	v_pk_fma_f32 v[58:59], v[58:59], v[144:145], v[170:171]
	v_pk_fma_f32 v[60:61], v[60:61], v[136:137], v[172:173]
	v_pk_fma_f32 v[54:55], v[54:55], v[154:155], v[174:175]
	v_pk_fma_f32 v[56:57], v[56:57], v[152:153], v[176:177]
	v_pk_fma_f32 v[50:51], v[50:51], v[150:151], v[178:179]
	v_pk_fma_f32 v[52:53], v[52:53], v[148:149], v[180:181]
	s_mov_b64 s[48:49], 0x80000
	v_lshl_add_u64 v[234:235], v[162:163], 0, s[48:49]
	global_store_dwordx4 v[234:235], v[62:65], off
	global_store_dwordx4 v[234:235], v[58:61], off offset:16
	global_store_dwordx4 v[234:235], v[54:57], off offset:512
	global_store_dwordx4 v[234:235], v[50:53], off offset:528
	s_mov_b64 s[48:49], 0xa0000
	v_lshl_add_u64 v[230:231], v[156:157], 0, s[48:49]
	global_load_dwordx4 v[166:169], v[230:231], off
	global_load_dwordx4 v[170:173], v[230:231], off offset:16
	global_load_dwordx4 v[174:177], v[230:231], off offset:512
	global_load_dwordx4 v[178:181], v[230:231], off offset:528
	s_waitcnt vmcnt(8)
	v_pk_fma_f32 v[46:47], v[46:47], v[160:161], v[208:209]
	v_pk_fma_f32 v[48:49], v[48:49], v[158:159], v[210:211]
	v_pk_fma_f32 v[42:43], v[42:43], v[144:145], v[212:213]
	v_pk_fma_f32 v[44:45], v[44:45], v[136:137], v[214:215]
	v_pk_fma_f32 v[38:39], v[38:39], v[154:155], v[216:217]
	v_pk_fma_f32 v[40:41], v[40:41], v[152:153], v[218:219]
	v_pk_fma_f32 v[34:35], v[34:35], v[150:151], v[220:221]
	v_pk_fma_f32 v[36:37], v[36:37], v[148:149], v[222:223]
	s_mov_b64 s[48:49], 0x90000
	v_lshl_add_u64 v[234:235], v[162:163], 0, s[48:49]
	global_store_dwordx4 v[234:235], v[46:49], off
	global_store_dwordx4 v[234:235], v[42:45], off offset:16
	global_store_dwordx4 v[234:235], v[38:41], off offset:512
	global_store_dwordx4 v[234:235], v[34:37], off offset:528
	s_mov_b64 s[48:49], 0xb0000
	v_lshl_add_u64 v[232:233], v[156:157], 0, s[48:49]
	global_load_dwordx4 v[208:211], v[232:233], off
	global_load_dwordx4 v[212:215], v[232:233], off offset:16
	global_load_dwordx4 v[216:219], v[232:233], off offset:512
	global_load_dwordx4 v[220:223], v[232:233], off offset:528
	s_waitcnt vmcnt(8)
	v_pk_fma_f32 v[30:31], v[30:31], v[160:161], v[166:167]
	v_pk_fma_f32 v[32:33], v[32:33], v[158:159], v[168:169]
	v_pk_fma_f32 v[26:27], v[26:27], v[144:145], v[170:171]
	v_pk_fma_f32 v[28:29], v[28:29], v[136:137], v[172:173]
	v_pk_fma_f32 v[22:23], v[22:23], v[154:155], v[174:175]
	v_pk_fma_f32 v[24:25], v[24:25], v[152:153], v[176:177]
	v_pk_fma_f32 v[18:19], v[18:19], v[150:151], v[178:179]
	v_pk_fma_f32 v[20:21], v[20:21], v[148:149], v[180:181]
	s_mov_b64 s[48:49], 0xa0000
	v_lshl_add_u64 v[234:235], v[162:163], 0, s[48:49]
	global_store_dwordx4 v[234:235], v[30:33], off
	global_store_dwordx4 v[234:235], v[26:29], off offset:16
	global_store_dwordx4 v[234:235], v[22:25], off offset:512
	global_store_dwordx4 v[234:235], v[18:21], off offset:528
	s_waitcnt vmcnt(4)
	v_pk_fma_f32 v[14:15], v[14:15], v[160:161], v[208:209]
	v_pk_fma_f32 v[16:17], v[16:17], v[158:159], v[210:211]
	v_pk_fma_f32 v[10:11], v[10:11], v[144:145], v[212:213]
	v_pk_fma_f32 v[12:13], v[12:13], v[136:137], v[214:215]
	v_pk_fma_f32 v[6:7], v[6:7], v[154:155], v[216:217]
	v_pk_fma_f32 v[8:9], v[8:9], v[152:153], v[218:219]
	v_pk_fma_f32 v[2:3], v[2:3], v[150:151], v[220:221]
	v_pk_fma_f32 v[4:5], v[4:5], v[148:149], v[222:223]
	s_mov_b64 s[48:49], 0xb0000
	v_lshl_add_u64 v[234:235], v[162:163], 0, s[48:49]
	global_store_dwordx4 v[234:235], v[14:17], off
	global_store_dwordx4 v[234:235], v[10:13], off offset:16
	global_store_dwordx4 v[234:235], v[6:9], off offset:512
	global_store_dwordx4 v[234:235], v[2:5], off offset:528
	s_mov_b64 s[48:49], -1
	s_branch .Lkq_epi_end

; __device__ __forceinline__ unsigned xb_ld(unsigned* p)              { return __hip_atomic_load(p, __ATOMIC_RELAXED, __HIP_MEMORY_SCOPE_AGENT); }
; __device__ __forceinline__ void xcd_barrier_complete(unsigned* bar, unsigned x, unsigned& nloc, unsigned& nx) {
;     ...
;         sum = 0u; cnt = 0u; mine = 0u;
; #pragma unroll
;         for (unsigned j = 0; j < 16; ++j) { const unsigned c = xb_ld(&bar[XB_XCNT(j)]); sum += c; cnt += (c > 0u) ? 1u : 0u; mine = (j == x) ? c : mine; }
;         if (sum == G) break;
;         __builtin_amdgcn_s_sleep(1);
;         if ((++sp & 255u) == 0u) { if (xb_ld(&bar[XB_TMO])) break; if (sp > XB_SPIN_CAP) { atomicAdd(&bar[XB_TMO], 1u); break; } }
;     }
.LBB0_971:
	s_cmp_lt_u32 s20, 0x40001
	s_mov_b64 s[16:17], 0
	s_cselect_b64 s[18:19], -1, 0
	s_and_b64 vcc, exec, s[18:19]
	s_cbranch_vccnz .LBB0_968
	s_branch .LBB0_965
	s_nop 0
	s_nop 0
